# attnA V^T LDS bank conflicts removed: rows with e bit 4 set store the two 8-byte halves of each 16-byte chunk exchanged; PV ds_read_b64 address flips the half for those lanes
# baseline (speedup 1.0000x reference)
.LBB0_1261:
	ds_read2_b32 v[140:141], v219 offset1:32
	ds_read2_b32 v[136:137], v219 offset0:64 offset1:96
	v_and_b32_e32 v0, 1, v199
	v_and_b32_e32 v228, 63, v198
	v_mov_b32_e32 v142, v199
	v_mov_b32_e32 v139, v202
	v_mov_b32_e32 v130, v200
	v_bfe_u32 v131, v199, 1, 1
	v_mov_b32_e32 v135, v201
	s_lshl_b32 s1, s6, 8
	v_readfirstlane_b32 s0, v131
	s_lshl_b32 s3, s0, 7
	s_add_i32 s3, s3, s1
	v_lshl_add_u32 v134, v130, 7, s2
	v_lshlrev_b32_e32 v0, 6, v0
	v_lshlrev_b32_e32 v130, 2, v139
	v_add_u32_e32 v138, s3, v0
	s_mov_b64 s[0:1], -1
	s_cmpk_gt_i32 s3, 0x7ff
	v_ashrrev_i32_e32 v131, 31, v130
	s_cbranch_scc0 .LBB0_1263
	v_readfirstlane_b32 s8, v204
	s_lshr_b32 s8, s8, 6
	s_and_b32 s9, s8, 1
	s_lshr_b32 s10, s8, 2
	s_lshl_b32 s11, s9, 6
	s_add_i32 s11, s11, s3
	s_sub_i32 s11, s11, 0x800
	s_lshr_b32 s12, s11, 7
	s_and_b32 s11, s11, 0x7f
	s_lshl_b32 s10, s10, 7
	s_add_i32 s10, s10, s2
	s_lshr_b32 s13, s10, 12
	s_and_b32 s10, s10, 0xfff
	s_lshl_b32 s13, s13, 3
	s_add_i32 s13, s13, s12
	s_lshl_b32 s13, s13, 7
	s_add_i32 s13, s13, s11
	s_lshl_b32 s13, s13, 13
	s_lshl_b32 s10, s10, 1
	s_add_u32 s13, s13, s10
	v_readlane_b32 s14, v252, 27
	v_readlane_b32 s15, v252, 28
	s_add_u32 s14, s14, s13
	s_addc_u32 s15, s15, 0
	v_and_b32_e32 v130, 63, v204
	v_and_b32_e32 v131, 31, v130
	v_lshrrev_b32_e32 v132, 5, v130
	s_lshl_b32 s8, s8, 14
	v_lshlrev_b32_e32 v133, 10, v132
	v_lshl_add_u32 v133, v131, 1, v133
	v_add_u32_e32 v133, s8, v133
	v_lshrrev_b32_e32 v134, 4, v130
	v_and_b32_e32 v135, 15, v130
	v_lshlrev_b32_e32 v135, 4, v135
	v_lshl_add_u32 v138, v134, 8, v135
	v_add_u32_e32 v138, s8, v138
	v_lshl_add_u32 v139, v134, 13, v135
	s_waitcnt lgkmcnt(0)
	v_mul_f32_e32 v142, v98, v140
	v_mul_f32_e32 v143, v99, v140
	v_cvt_pk_bf16_f32 v142, v142, v143
	ds_write_b16 v133, v142 offset:0
	ds_write_b16_d16_hi v133, v142 offset:256
	v_mul_f32_e32 v144, v100, v140
	v_mul_f32_e32 v145, v101, v140
	v_cvt_pk_bf16_f32 v144, v144, v145
	ds_write_b16 v133, v144 offset:512
	ds_write_b16_d16_hi v133, v144 offset:768
	v_mul_f32_e32 v146, v102, v140
	v_mul_f32_e32 v147, v103, v140
	v_cvt_pk_bf16_f32 v146, v146, v147
	ds_write_b16 v133, v146 offset:2048
	ds_write_b16_d16_hi v133, v146 offset:2304
	v_mul_f32_e32 v148, v104, v140
	v_mul_f32_e32 v149, v105, v140
	v_cvt_pk_bf16_f32 v148, v148, v149
	ds_write_b16 v133, v148 offset:2560
	ds_write_b16_d16_hi v133, v148 offset:2816
	v_mul_f32_e32 v142, v106, v140
	v_mul_f32_e32 v143, v107, v140
	v_cvt_pk_bf16_f32 v142, v142, v143
	ds_write_b16 v133, v142 offset:4096
	ds_write_b16_d16_hi v133, v142 offset:4352
	v_mul_f32_e32 v144, v108, v140
	v_mul_f32_e32 v145, v109, v140
	v_cvt_pk_bf16_f32 v144, v144, v145
	ds_write_b16 v133, v144 offset:4608
	ds_write_b16_d16_hi v133, v144 offset:4864
	v_mul_f32_e32 v146, v110, v140
	v_mul_f32_e32 v147, v111, v140
	v_cvt_pk_bf16_f32 v146, v146, v147
	ds_write_b16 v133, v146 offset:6144
	ds_write_b16_d16_hi v133, v146 offset:6400
	v_mul_f32_e32 v148, v112, v140
	v_mul_f32_e32 v149, v113, v140
	v_cvt_pk_bf16_f32 v148, v148, v149
	ds_write_b16 v133, v148 offset:6656
	ds_write_b16_d16_hi v133, v148 offset:6912
	v_mul_f32_e32 v142, v114, v140
	v_mul_f32_e32 v143, v115, v140
	v_cvt_pk_bf16_f32 v142, v142, v143
	ds_write_b16 v133, v142 offset:8192
	ds_write_b16_d16_hi v133, v142 offset:8448
	v_mul_f32_e32 v144, v116, v140
	v_mul_f32_e32 v145, v117, v140
	v_cvt_pk_bf16_f32 v144, v144, v145
	ds_write_b16 v133, v144 offset:8704
	ds_write_b16_d16_hi v133, v144 offset:8960
	v_mul_f32_e32 v146, v118, v140
	v_mul_f32_e32 v147, v119, v140
	v_cvt_pk_bf16_f32 v146, v146, v147
	ds_write_b16 v133, v146 offset:10240
	ds_write_b16_d16_hi v133, v146 offset:10496
	v_mul_f32_e32 v148, v120, v140
	v_mul_f32_e32 v149, v121, v140
	v_cvt_pk_bf16_f32 v148, v148, v149
	ds_write_b16 v133, v148 offset:10752
	ds_write_b16_d16_hi v133, v148 offset:11008
	v_mul_f32_e32 v142, v122, v140
	v_mul_f32_e32 v143, v123, v140
	v_cvt_pk_bf16_f32 v142, v142, v143
	ds_write_b16 v133, v142 offset:12288
	ds_write_b16_d16_hi v133, v142 offset:12544
	v_mul_f32_e32 v144, v124, v140
	v_mul_f32_e32 v145, v125, v140
	v_cvt_pk_bf16_f32 v144, v144, v145
	ds_write_b16 v133, v144 offset:12800
	ds_write_b16_d16_hi v133, v144 offset:13056
	v_mul_f32_e32 v146, v126, v140
	v_mul_f32_e32 v147, v127, v140
	v_cvt_pk_bf16_f32 v146, v146, v147
	ds_write_b16 v133, v146 offset:14336
	ds_write_b16_d16_hi v133, v146 offset:14592
	v_mul_f32_e32 v148, v128, v140
	v_mul_f32_e32 v149, v129, v140
	v_cvt_pk_bf16_f32 v148, v148, v149
	ds_write_b16 v133, v148 offset:14848
	ds_write_b16_d16_hi v133, v148 offset:15104
	v_mul_f32_e32 v142, v82, v141
	v_mul_f32_e32 v143, v83, v141
	v_cvt_pk_bf16_f32 v142, v142, v143
	ds_write_b16 v133, v142 offset:64
	ds_write_b16_d16_hi v133, v142 offset:320
	v_mul_f32_e32 v144, v84, v141
	v_mul_f32_e32 v145, v85, v141
	v_cvt_pk_bf16_f32 v144, v144, v145
	ds_write_b16 v133, v144 offset:576
	ds_write_b16_d16_hi v133, v144 offset:832
	v_mul_f32_e32 v146, v86, v141
	v_mul_f32_e32 v147, v87, v141
	v_cvt_pk_bf16_f32 v146, v146, v147
	ds_write_b16 v133, v146 offset:2112
	ds_write_b16_d16_hi v133, v146 offset:2368
	v_mul_f32_e32 v148, v88, v141
	v_mul_f32_e32 v149, v89, v141
	v_cvt_pk_bf16_f32 v148, v148, v149
	ds_write_b16 v133, v148 offset:2624
	ds_write_b16_d16_hi v133, v148 offset:2880
	v_mul_f32_e32 v142, v90, v141
	v_mul_f32_e32 v143, v91, v141
	v_cvt_pk_bf16_f32 v142, v142, v143
	ds_write_b16 v133, v142 offset:4160
	ds_write_b16_d16_hi v133, v142 offset:4416
	v_mul_f32_e32 v144, v92, v141
	v_mul_f32_e32 v145, v93, v141
	v_cvt_pk_bf16_f32 v144, v144, v145
	ds_write_b16 v133, v144 offset:4672
	ds_write_b16_d16_hi v133, v144 offset:4928
	v_mul_f32_e32 v146, v94, v141
	v_mul_f32_e32 v147, v95, v141
	v_cvt_pk_bf16_f32 v146, v146, v147
	ds_write_b16 v133, v146 offset:6208
	ds_write_b16_d16_hi v133, v146 offset:6464
	v_mul_f32_e32 v148, v96, v141
	v_mul_f32_e32 v149, v97, v141
	v_cvt_pk_bf16_f32 v148, v148, v149
	ds_write_b16 v133, v148 offset:6720
	ds_write_b16_d16_hi v133, v148 offset:6976
	v_mul_f32_e32 v142, v66, v141
	v_mul_f32_e32 v143, v67, v141
	v_cvt_pk_bf16_f32 v142, v142, v143
	ds_write_b16 v133, v142 offset:8256
	ds_write_b16_d16_hi v133, v142 offset:8512
	v_mul_f32_e32 v144, v68, v141
	v_mul_f32_e32 v145, v69, v141
	v_cvt_pk_bf16_f32 v144, v144, v145
	ds_write_b16 v133, v144 offset:8768
	ds_write_b16_d16_hi v133, v144 offset:9024
	v_mul_f32_e32 v146, v70, v141
	v_mul_f32_e32 v147, v71, v141
	v_cvt_pk_bf16_f32 v146, v146, v147
	ds_write_b16 v133, v146 offset:10304
	ds_write_b16_d16_hi v133, v146 offset:10560
	v_mul_f32_e32 v148, v72, v141
	v_mul_f32_e32 v149, v73, v141
	v_cvt_pk_bf16_f32 v148, v148, v149
	ds_write_b16 v133, v148 offset:10816
	ds_write_b16_d16_hi v133, v148 offset:11072
	v_mul_f32_e32 v142, v74, v141
	v_mul_f32_e32 v143, v75, v141
	v_cvt_pk_bf16_f32 v142, v142, v143
	ds_write_b16 v133, v142 offset:12352
	ds_write_b16_d16_hi v133, v142 offset:12608
	v_mul_f32_e32 v144, v76, v141
	v_mul_f32_e32 v145, v77, v141
	v_cvt_pk_bf16_f32 v144, v144, v145
	ds_write_b16 v133, v144 offset:12864
	ds_write_b16_d16_hi v133, v144 offset:13120
	v_mul_f32_e32 v146, v78, v141
	v_mul_f32_e32 v147, v79, v141
	v_cvt_pk_bf16_f32 v146, v146, v147
	ds_write_b16 v133, v146 offset:14400
	ds_write_b16_d16_hi v133, v146 offset:14656
	v_mul_f32_e32 v148, v80, v141
	v_mul_f32_e32 v149, v81, v141
	v_cvt_pk_bf16_f32 v148, v148, v149
	ds_write_b16 v133, v148 offset:14912
	ds_write_b16_d16_hi v133, v148 offset:15168
	v_mul_f32_e32 v142, v34, v136
	v_mul_f32_e32 v143, v35, v136
	v_cvt_pk_bf16_f32 v142, v142, v143
	ds_write_b16 v133, v142 offset:128
	ds_write_b16_d16_hi v133, v142 offset:384
	v_mul_f32_e32 v144, v36, v136
	v_mul_f32_e32 v145, v37, v136
	v_cvt_pk_bf16_f32 v144, v144, v145
	ds_write_b16 v133, v144 offset:640
	ds_write_b16_d16_hi v133, v144 offset:896
	v_mul_f32_e32 v146, v38, v136
	v_mul_f32_e32 v147, v39, v136
	v_cvt_pk_bf16_f32 v146, v146, v147
	ds_write_b16 v133, v146 offset:2176
	ds_write_b16_d16_hi v133, v146 offset:2432
	v_mul_f32_e32 v148, v40, v136
	v_mul_f32_e32 v149, v41, v136
	v_cvt_pk_bf16_f32 v148, v148, v149
	ds_write_b16 v133, v148 offset:2688
	ds_write_b16_d16_hi v133, v148 offset:2944
	v_mul_f32_e32 v142, v42, v136
	v_mul_f32_e32 v143, v43, v136
	v_cvt_pk_bf16_f32 v142, v142, v143
	ds_write_b16 v133, v142 offset:4224
	ds_write_b16_d16_hi v133, v142 offset:4480
	v_mul_f32_e32 v144, v44, v136
	v_mul_f32_e32 v145, v45, v136
	v_cvt_pk_bf16_f32 v144, v144, v145
	ds_write_b16 v133, v144 offset:4736
	ds_write_b16_d16_hi v133, v144 offset:4992
	v_mul_f32_e32 v146, v46, v136
	v_mul_f32_e32 v147, v47, v136
	v_cvt_pk_bf16_f32 v146, v146, v147
	ds_write_b16 v133, v146 offset:6272
	ds_write_b16_d16_hi v133, v146 offset:6528
	v_mul_f32_e32 v148, v48, v136
	v_mul_f32_e32 v149, v49, v136
	v_cvt_pk_bf16_f32 v148, v148, v149
	ds_write_b16 v133, v148 offset:6784
	ds_write_b16_d16_hi v133, v148 offset:7040
	v_mul_f32_e32 v142, v50, v136
	v_mul_f32_e32 v143, v51, v136
	v_cvt_pk_bf16_f32 v142, v142, v143
	ds_write_b16 v133, v142 offset:8320
	ds_write_b16_d16_hi v133, v142 offset:8576
	v_mul_f32_e32 v144, v52, v136
	v_mul_f32_e32 v145, v53, v136
	v_cvt_pk_bf16_f32 v144, v144, v145
	ds_write_b16 v133, v144 offset:8832
	ds_write_b16_d16_hi v133, v144 offset:9088
	v_mul_f32_e32 v146, v54, v136
	v_mul_f32_e32 v147, v55, v136
	v_cvt_pk_bf16_f32 v146, v146, v147
	ds_write_b16 v133, v146 offset:10368
	ds_write_b16_d16_hi v133, v146 offset:10624
	v_mul_f32_e32 v148, v56, v136
	v_mul_f32_e32 v149, v57, v136
	v_cvt_pk_bf16_f32 v148, v148, v149
	ds_write_b16 v133, v148 offset:10880
	ds_write_b16_d16_hi v133, v148 offset:11136
	v_mul_f32_e32 v142, v58, v136
	v_mul_f32_e32 v143, v59, v136
	v_cvt_pk_bf16_f32 v142, v142, v143
	ds_write_b16 v133, v142 offset:12416
	ds_write_b16_d16_hi v133, v142 offset:12672
	v_mul_f32_e32 v144, v60, v136
	v_mul_f32_e32 v145, v61, v136
	v_cvt_pk_bf16_f32 v144, v144, v145
	ds_write_b16 v133, v144 offset:12928
	ds_write_b16_d16_hi v133, v144 offset:13184
	v_mul_f32_e32 v146, v62, v136
	v_mul_f32_e32 v147, v63, v136
	v_cvt_pk_bf16_f32 v146, v146, v147
	ds_write_b16 v133, v146 offset:14464
	ds_write_b16_d16_hi v133, v146 offset:14720
	v_mul_f32_e32 v148, v64, v136
	v_mul_f32_e32 v149, v65, v136
	v_cvt_pk_bf16_f32 v148, v148, v149
	ds_write_b16 v133, v148 offset:14976
	ds_write_b16_d16_hi v133, v148 offset:15232
	v_mul_f32_e32 v142, v18, v137
	v_mul_f32_e32 v143, v19, v137
	v_cvt_pk_bf16_f32 v142, v142, v143
	ds_write_b16 v133, v142 offset:192
	ds_write_b16_d16_hi v133, v142 offset:448
	v_mul_f32_e32 v144, v20, v137
	v_mul_f32_e32 v145, v21, v137
	v_cvt_pk_bf16_f32 v144, v144, v145
	ds_write_b16 v133, v144 offset:704
	ds_write_b16_d16_hi v133, v144 offset:960
	v_mul_f32_e32 v146, v22, v137
	v_mul_f32_e32 v147, v23, v137
	v_cvt_pk_bf16_f32 v146, v146, v147
	ds_write_b16 v133, v146 offset:2240
	ds_write_b16_d16_hi v133, v146 offset:2496
	v_mul_f32_e32 v148, v24, v137
	v_mul_f32_e32 v149, v25, v137
	v_cvt_pk_bf16_f32 v148, v148, v149
	ds_write_b16 v133, v148 offset:2752
	ds_write_b16_d16_hi v133, v148 offset:3008
	v_mul_f32_e32 v142, v26, v137
	v_mul_f32_e32 v143, v27, v137
	v_cvt_pk_bf16_f32 v142, v142, v143
	ds_write_b16 v133, v142 offset:4288
	ds_write_b16_d16_hi v133, v142 offset:4544
	v_mul_f32_e32 v144, v28, v137
	v_mul_f32_e32 v145, v29, v137
	v_cvt_pk_bf16_f32 v144, v144, v145
	ds_write_b16 v133, v144 offset:4800
	ds_write_b16_d16_hi v133, v144 offset:5056
	v_mul_f32_e32 v146, v30, v137
	v_mul_f32_e32 v147, v31, v137
	v_cvt_pk_bf16_f32 v146, v146, v147
	ds_write_b16 v133, v146 offset:6336
	ds_write_b16_d16_hi v133, v146 offset:6592
	v_mul_f32_e32 v148, v32, v137
	v_mul_f32_e32 v149, v33, v137
	v_cvt_pk_bf16_f32 v148, v148, v149
	ds_write_b16 v133, v148 offset:6848
	ds_write_b16_d16_hi v133, v148 offset:7104
	v_mul_f32_e32 v142, v2, v137
	v_mul_f32_e32 v143, v3, v137
	v_cvt_pk_bf16_f32 v142, v142, v143
	ds_write_b16 v133, v142 offset:8384
	ds_write_b16_d16_hi v133, v142 offset:8640
	v_mul_f32_e32 v144, v4, v137
	v_mul_f32_e32 v145, v5, v137
	v_cvt_pk_bf16_f32 v144, v144, v145
	ds_write_b16 v133, v144 offset:8896
	ds_write_b16_d16_hi v133, v144 offset:9152
	v_mul_f32_e32 v146, v6, v137
	v_mul_f32_e32 v147, v7, v137
	v_cvt_pk_bf16_f32 v146, v146, v147
	ds_write_b16 v133, v146 offset:10432
	ds_write_b16_d16_hi v133, v146 offset:10688
	v_mul_f32_e32 v148, v8, v137
	v_mul_f32_e32 v149, v9, v137
	v_cvt_pk_bf16_f32 v148, v148, v149
	ds_write_b16 v133, v148 offset:10944
	ds_write_b16_d16_hi v133, v148 offset:11200
	v_mul_f32_e32 v142, v10, v137
	v_mul_f32_e32 v143, v11, v137
	v_cvt_pk_bf16_f32 v142, v142, v143
	ds_write_b16 v133, v142 offset:12480
	ds_write_b16_d16_hi v133, v142 offset:12736
	v_mul_f32_e32 v144, v12, v137
	v_mul_f32_e32 v145, v13, v137
	v_cvt_pk_bf16_f32 v144, v144, v145
	ds_write_b16 v133, v144 offset:12992
	ds_write_b16_d16_hi v133, v144 offset:13248
	v_mul_f32_e32 v146, v14, v137
	v_mul_f32_e32 v147, v15, v137
	v_cvt_pk_bf16_f32 v146, v146, v147
	ds_write_b16 v133, v146 offset:14528
	ds_write_b16_d16_hi v133, v146 offset:14784
	v_mul_f32_e32 v148, v16, v137
	v_mul_f32_e32 v149, v17, v137
	v_cvt_pk_bf16_f32 v148, v148, v149
	ds_write_b16 v133, v148 offset:15040
	ds_write_b16_d16_hi v133, v148 offset:15296
	s_waitcnt lgkmcnt(0)
	ds_read_b128 v[144:147], v138 offset:0
	ds_read_b128 v[148:151], v138 offset:1024
	ds_read_b128 v[152:155], v138 offset:2048
	ds_read_b128 v[156:159], v138 offset:3072
	s_waitcnt lgkmcnt(3)
	global_store_dwordx4 v139, v[144:147], s[14:15]
	s_waitcnt lgkmcnt(2)
	v_add_u32_e32 v161, 0x8000, v139
	global_store_dwordx4 v161, v[148:151], s[14:15]
	s_waitcnt lgkmcnt(1)
	v_add_u32_e32 v162, 0x10000, v139
	global_store_dwordx4 v162, v[152:155], s[14:15]
	s_waitcnt lgkmcnt(0)
	v_add_u32_e32 v163, 0x18000, v139
	global_store_dwordx4 v163, v[156:159], s[14:15]
	s_nop 1
	ds_read_b64 v[144:145], v138 offset:4104
	ds_read_b64 v[146:147], v138 offset:4096
	ds_read_b64 v[148:149], v138 offset:5128
	ds_read_b64 v[150:151], v138 offset:5120
	ds_read_b64 v[152:153], v138 offset:6152
	ds_read_b64 v[154:155], v138 offset:6144
	ds_read_b64 v[156:157], v138 offset:7176
	ds_read_b64 v[158:159], v138 offset:7168
	s_waitcnt lgkmcnt(6)
	v_add_u32_e32 v160, 0x20000, v139
	global_store_dwordx4 v160, v[144:147], s[14:15]
	s_waitcnt lgkmcnt(4)
	v_add_u32_e32 v161, 0x28000, v139
	global_store_dwordx4 v161, v[148:151], s[14:15]
	s_waitcnt lgkmcnt(2)
	v_add_u32_e32 v162, 0x30000, v139
	global_store_dwordx4 v162, v[152:155], s[14:15]
	s_waitcnt lgkmcnt(0)
	v_add_u32_e32 v163, 0x38000, v139
	global_store_dwordx4 v163, v[156:159], s[14:15]
	s_nop 1
	ds_read_b128 v[144:147], v138 offset:8192
	ds_read_b128 v[148:151], v138 offset:9216
	ds_read_b128 v[152:155], v138 offset:10240
	ds_read_b128 v[156:159], v138 offset:11264
	s_waitcnt lgkmcnt(3)
	v_add_u32_e32 v160, 0x40000, v139
	global_store_dwordx4 v160, v[144:147], s[14:15]
	s_waitcnt lgkmcnt(2)
	v_add_u32_e32 v161, 0x48000, v139
	global_store_dwordx4 v161, v[148:151], s[14:15]
	s_waitcnt lgkmcnt(1)
	v_add_u32_e32 v162, 0x50000, v139
	global_store_dwordx4 v162, v[152:155], s[14:15]
	s_waitcnt lgkmcnt(0)
	v_add_u32_e32 v163, 0x58000, v139
	global_store_dwordx4 v163, v[156:159], s[14:15]
	s_nop 1
	ds_read_b64 v[144:145], v138 offset:12296
	ds_read_b64 v[146:147], v138 offset:12288
	ds_read_b64 v[148:149], v138 offset:13320
	ds_read_b64 v[150:151], v138 offset:13312
	ds_read_b64 v[152:153], v138 offset:14344
	ds_read_b64 v[154:155], v138 offset:14336
	ds_read_b64 v[156:157], v138 offset:15368
	ds_read_b64 v[158:159], v138 offset:15360
	s_waitcnt lgkmcnt(6)
	v_add_u32_e32 v160, 0x60000, v139
	global_store_dwordx4 v160, v[144:147], s[14:15]
	s_waitcnt lgkmcnt(4)
	v_add_u32_e32 v161, 0x68000, v139
	global_store_dwordx4 v161, v[148:151], s[14:15]
	s_waitcnt lgkmcnt(2)
	v_add_u32_e32 v162, 0x70000, v139
	global_store_dwordx4 v162, v[152:155], s[14:15]
	s_waitcnt lgkmcnt(0)
	v_add_u32_e32 v163, 0x78000, v139
	global_store_dwordx4 v163, v[156:159], s[14:15]
	s_nop 1
	s_mov_b64 s[0:1], 0

.LBB0_1366:
	s_lshl_b32 s29, s18, 1
	v_ashrrev_i32_e32 v2, 7, v2
	v_lshlrev_b32_e32 v3, 3, v3
	v_add_u32_e32 v226, s29, v2
	v_lshlrev_b32_e32 v2, 4, v4
	v_add_u32_e32 v64, s80, v3
	v_and_b32_e32 v14, 16, v214
	v_lshrrev_b32_e32 v14, 1, v14
	v_xor_b32_e32 v64, v64, v14
	v_or_b32_e32 v65, v2, v0
	v_bitop3_b32 v66, v2, v0, 16 bitop3:0xde
	v_add_u32_e32 v67, v0, v2
	v_xad_u32 v68, v2, 16, v0
	v_bitop3_b32 v69, v2, v0, 32 bitop3:0xde
	v_bitop3_b32 v70, v2, v0, 48 bitop3:0xde
	v_xad_u32 v71, v2, 32, v0
	v_xad_u32 v72, v2, 48, v0
	v_bitop3_b32 v73, v2, v0, 64 bitop3:0xde
	v_bitop3_b32 v74, v2, v0, s70 bitop3:0xde
	v_xad_u32 v75, v2, 64, v0
	v_xad_u32 v76, v2, s70, v0
	v_bitop3_b32 v77, v2, v0, s63 bitop3:0xde
	v_bitop3_b32 v78, v2, v0, s55 bitop3:0xde
	v_xad_u32 v79, v2, s63, v0
	v_xad_u32 v80, v2, s55, v0
	v_mov_b32_e32 v14, v1
	v_mov_b32_e32 v15, v1
	v_mov_b32_e32 v0, v1
	v_mov_b32_e32 v2, v1
	v_mov_b32_e32 v3, v1
	v_mov_b32_e32 v4, v1
	v_mov_b32_e32 v5, v1
	v_mov_b32_e32 v6, v1
	v_mov_b32_e32 v7, v1
	v_mov_b32_e32 v8, v1
	v_mov_b32_e32 v9, v1
	v_mov_b32_e32 v10, v1
	v_mov_b32_e32 v11, v1
	v_mov_b32_e32 v12, v1
	v_mov_b32_e32 v13, v1
	v_add_u32_e32 v228, v64, v65
	v_add_u32_e32 v229, v64, v66
	v_add_u32_e32 v230, v64, v67
	v_add_u32_e32 v231, v64, v68
	v_add_u32_e32 v232, v64, v69
	v_add_u32_e32 v233, v64, v70
	v_add_u32_e32 v234, v64, v71
	v_add_u32_e32 v235, v64, v72
	v_add_u32_e32 v236, v64, v73
	v_add_u32_e32 v237, v64, v74
	v_add_u32_e32 v238, v64, v75
	v_add_u32_e32 v239, v64, v76
	v_add_u32_e32 v240, v64, v77
	v_add_u32_e32 v241, v64, v78
	v_add_u32_e32 v242, v64, v79
	v_add_u32_e32 v243, v64, v80
	v_mov_b64_e32 v[78:79], v[14:15]
	v_mov_b64_e32 v[94:95], v[14:15]
	v_mov_b64_e32 v[110:111], v[14:15]
	v_mov_b64_e32 v[126:127], v[14:15]
	v_mov_b64_e32 v[158:159], v[14:15]
	v_mov_b64_e32 v[142:143], v[14:15]
	s_xor_b64 s[14:15], s[4:5], -1
	s_add_i32 s30, s29, 2
	s_mov_b32 s34, 0
	v_mov_b32_e32 v227, 0
	v_mov_b64_e32 v[76:77], v[12:13]
	v_mov_b64_e32 v[74:75], v[10:11]
	v_mov_b64_e32 v[72:73], v[8:9]
	v_mov_b64_e32 v[70:71], v[6:7]
	v_mov_b64_e32 v[68:69], v[4:5]
	v_mov_b64_e32 v[66:67], v[2:3]
	v_mov_b64_e32 v[64:65], v[0:1]
	v_mov_b64_e32 v[92:93], v[12:13]
	v_mov_b64_e32 v[90:91], v[10:11]
	v_mov_b64_e32 v[88:89], v[8:9]
	v_mov_b64_e32 v[86:87], v[6:7]
	v_mov_b64_e32 v[84:85], v[4:5]
	v_mov_b64_e32 v[82:83], v[2:3]
	v_mov_b64_e32 v[80:81], v[0:1]
	v_mov_b64_e32 v[108:109], v[12:13]
	v_mov_b64_e32 v[106:107], v[10:11]
	v_mov_b64_e32 v[104:105], v[8:9]
	v_mov_b64_e32 v[102:103], v[6:7]
	v_mov_b64_e32 v[100:101], v[4:5]
	v_mov_b64_e32 v[98:99], v[2:3]
	v_mov_b64_e32 v[96:97], v[0:1]
	v_mov_b64_e32 v[124:125], v[12:13]
	v_mov_b64_e32 v[122:123], v[10:11]
	v_mov_b64_e32 v[120:121], v[8:9]
	v_mov_b64_e32 v[118:119], v[6:7]
	v_mov_b64_e32 v[116:117], v[4:5]
	v_mov_b64_e32 v[114:115], v[2:3]
	v_mov_b64_e32 v[112:113], v[0:1]
	v_mov_b64_e32 v[156:157], v[12:13]
	v_mov_b64_e32 v[154:155], v[10:11]
	v_mov_b64_e32 v[152:153], v[8:9]
	v_mov_b64_e32 v[150:151], v[6:7]
	v_mov_b64_e32 v[148:149], v[4:5]
	v_mov_b64_e32 v[146:147], v[2:3]
	v_mov_b64_e32 v[144:145], v[0:1]
	v_mov_b64_e32 v[140:141], v[12:13]
	v_mov_b64_e32 v[138:139], v[10:11]
	v_mov_b64_e32 v[136:137], v[8:9]
	v_mov_b64_e32 v[134:135], v[6:7]
	v_mov_b64_e32 v[132:133], v[4:5]
	v_mov_b64_e32 v[130:131], v[2:3]
	v_mov_b64_e32 v[128:129], v[0:1]

.LBB0_1408:
	v_ashrrev_i32_e32 v2, 7, v2
	v_lshlrev_b32_e32 v3, 3, v3
	v_add_u32_e32 v225, s29, v2
	v_lshlrev_b32_e32 v2, 4, v4
	v_add_u32_e32 v32, s80, v3
	v_and_b32_e32 v14, 16, v214
	v_lshrrev_b32_e32 v14, 1, v14
	v_xor_b32_e32 v32, v32, v14
	v_or_b32_e32 v33, v2, v0
	v_bitop3_b32 v34, v2, v0, 16 bitop3:0xde
	v_add_u32_e32 v35, v0, v2
	v_xad_u32 v36, v2, 16, v0
	v_bitop3_b32 v37, v2, v0, 32 bitop3:0xde
	v_bitop3_b32 v38, v2, v0, 48 bitop3:0xde
	v_xad_u32 v39, v2, 32, v0
	v_xad_u32 v40, v2, 48, v0
	v_bitop3_b32 v41, v2, v0, 64 bitop3:0xde
	v_bitop3_b32 v42, v2, v0, s70 bitop3:0xde
	v_xad_u32 v43, v2, 64, v0
	v_xad_u32 v44, v2, s70, v0
	v_bitop3_b32 v45, v2, v0, s63 bitop3:0xde
	v_bitop3_b32 v46, v2, v0, s55 bitop3:0xde
	v_xad_u32 v47, v2, s63, v0
	v_xad_u32 v48, v2, s55, v0
	v_mov_b32_e32 v14, v1
	v_mov_b32_e32 v15, v1
	v_mov_b32_e32 v0, v1
	v_mov_b32_e32 v2, v1
	v_mov_b32_e32 v3, v1
	v_mov_b32_e32 v4, v1
	v_mov_b32_e32 v5, v1
	v_mov_b32_e32 v6, v1
	v_mov_b32_e32 v7, v1
	v_mov_b32_e32 v8, v1
	v_mov_b32_e32 v9, v1
	v_mov_b32_e32 v10, v1
	v_mov_b32_e32 v11, v1
	v_mov_b32_e32 v12, v1
	v_mov_b32_e32 v13, v1
	v_add_u32_e32 v226, v32, v33
	v_add_u32_e32 v227, v32, v34
	v_add_u32_e32 v228, v32, v35
	v_add_u32_e32 v229, v32, v36
	v_add_u32_e32 v230, v32, v37
	v_add_u32_e32 v231, v32, v38
	v_add_u32_e32 v232, v32, v39
	v_add_u32_e32 v233, v32, v40
	v_add_u32_e32 v234, v32, v41
	v_add_u32_e32 v235, v32, v42
	v_add_u32_e32 v236, v32, v43
	v_add_u32_e32 v237, v32, v44
	v_add_u32_e32 v238, v32, v45
	v_add_u32_e32 v239, v32, v46
	v_add_u32_e32 v240, v32, v47
	v_add_u32_e32 v241, v32, v48
	v_mov_b64_e32 v[126:127], v[14:15]
	v_mov_b64_e32 v[46:47], v[14:15]
	v_mov_b64_e32 v[62:63], v[14:15]
	v_mov_b64_e32 v[78:79], v[14:15]
	v_mov_b64_e32 v[158:159], v[14:15]
	v_mov_b64_e32 v[142:143], v[14:15]
	s_mov_b32 s31, 0
	v_mov_b32_e32 v224, 0
	v_mov_b64_e32 v[124:125], v[12:13]
	v_mov_b64_e32 v[122:123], v[10:11]
	v_mov_b64_e32 v[120:121], v[8:9]
	v_mov_b64_e32 v[118:119], v[6:7]
	v_mov_b64_e32 v[116:117], v[4:5]
	v_mov_b64_e32 v[114:115], v[2:3]
	v_mov_b64_e32 v[112:113], v[0:1]
	v_mov_b64_e32 v[44:45], v[12:13]
	v_mov_b64_e32 v[42:43], v[10:11]
	v_mov_b64_e32 v[40:41], v[8:9]
	v_mov_b64_e32 v[38:39], v[6:7]
	v_mov_b64_e32 v[36:37], v[4:5]
	v_mov_b64_e32 v[34:35], v[2:3]
	v_mov_b64_e32 v[32:33], v[0:1]
	v_mov_b64_e32 v[60:61], v[12:13]
	v_mov_b64_e32 v[58:59], v[10:11]
	v_mov_b64_e32 v[56:57], v[8:9]
	v_mov_b64_e32 v[54:55], v[6:7]
	v_mov_b64_e32 v[52:53], v[4:5]
	v_mov_b64_e32 v[50:51], v[2:3]
	v_mov_b64_e32 v[48:49], v[0:1]
	v_mov_b64_e32 v[76:77], v[12:13]
	v_mov_b64_e32 v[74:75], v[10:11]
	v_mov_b64_e32 v[72:73], v[8:9]
	v_mov_b64_e32 v[70:71], v[6:7]
	v_mov_b64_e32 v[68:69], v[4:5]
	v_mov_b64_e32 v[66:67], v[2:3]
	v_mov_b64_e32 v[64:65], v[0:1]
	v_mov_b64_e32 v[156:157], v[12:13]
	v_mov_b64_e32 v[154:155], v[10:11]
	v_mov_b64_e32 v[152:153], v[8:9]
	v_mov_b64_e32 v[150:151], v[6:7]
	v_mov_b64_e32 v[148:149], v[4:5]
	v_mov_b64_e32 v[146:147], v[2:3]
	v_mov_b64_e32 v[144:145], v[0:1]
	v_mov_b64_e32 v[140:141], v[12:13]
	v_mov_b64_e32 v[138:139], v[10:11]
	v_mov_b64_e32 v[136:137], v[8:9]
	v_mov_b64_e32 v[134:135], v[6:7]
	v_mov_b64_e32 v[132:133], v[4:5]
	v_mov_b64_e32 v[130:131], v[2:3]
	v_mov_b64_e32 v[128:129], v[0:1]
